# grid barrier acquire: non-leaders invalidate at arrival, the last arriver releases first and invalidates after its release atomic
# speedup vs baseline: 1.0196x; 1.0034x over previous
; __device__ __forceinline__ unsigned xb_ld(unsigned* p)              { return __hip_atomic_load(p, __ATOMIC_RELAXED, __HIP_MEMORY_SCOPE_AGENT); }
; __device__ __forceinline__ unsigned xb_add(unsigned* p, unsigned v) { return __hip_atomic_fetch_add(p, v, __ATOMIC_RELAXED, __HIP_MEMORY_SCOPE_AGENT); }
; #define XB_SPIN(cond, bar) do { unsigned _sp = 0; while (cond) { __builtin_amdgcn_s_sleep(1); \
;     if ((++_sp & 255u) == 0u) { if (xb_ld(&(bar)[XB_TMO])) break; if (_sp > XB_SPIN_CAP) { atomicAdd(&(bar)[XB_TMO], 1u); break; } } } } while (0)
; __device__ __forceinline__ void xcd_barrier(const XcdBarrier& b) {
;     ...
;         const unsigned old = xb_add(&bar[XB_XSUB(b.x)], 1u);
;         const unsigned gen = old / nloc;
;         if (old + 1u == (gen + 1u) * nloc) {
;             __builtin_amdgcn_fence(__ATOMIC_RELEASE, "agent");
;             asm volatile("s_waitcnt vmcnt(0)" ::: "memory");
;             const unsigned og = xb_add(&bar[XB_TOP], 1u);
;             const unsigned tg = og / nx;
;             if (og + 1u == (tg + 1u) * nx) xb_add(&bar[XB_TOPGEN], 1u);
;             else XB_SPIN(xb_ld(&bar[XB_TOPGEN]) == tg, bar);
;             __builtin_amdgcn_fence(__ATOMIC_ACQUIRE, "agent");
;             xb_add(&bar[XB_XGEN(b.x)], 1u);
;             asm volatile("s_waitcnt vmcnt(0)" ::: "memory");
;         } else {
;             XB_SPIN(xb_ld(&bar[XB_XGEN(b.x)]) == gen, bar);
.LBB0_377:
	s_or_b64 exec, exec, s[6:7]
	v_cvt_f32_u32_e32 v5, v3
	s_waitcnt vmcnt(0)
	v_readfirstlane_b32 s4, v4
	v_sub_u32_e32 v4, 0, v3
	v_rcp_iflag_f32_e32 v5, v5
	v_add_u32_e32 v6, s4, v2
	v_mul_f32_e32 v5, 0x4f7ffffe, v5
	v_cvt_u32_f32_e32 v5, v5
	v_mul_lo_u32 v2, v4, v5
	v_mul_hi_u32 v2, v5, v2
	v_add_u32_e32 v2, v5, v2
	v_mul_hi_u32 v2, v6, v2
	v_mul_lo_u32 v4, v2, v3
	v_sub_u32_e32 v4, v6, v4
	v_add_u32_e32 v5, 1, v2
	v_sub_u32_e32 v7, v4, v3
	v_cmp_ge_u32_e32 vcc, v4, v3
	s_nop 1
	v_cndmask_b32_e32 v2, v2, v5, vcc
	v_cndmask_b32_e32 v4, v4, v7, vcc
	v_add_u32_e32 v5, 1, v2
	v_cmp_ge_u32_e32 vcc, v4, v3
	v_add_u32_e32 v4, 1, v6
	s_nop 0
	v_cndmask_b32_e32 v2, v2, v5, vcc
	v_mul_lo_u32 v5, v3, v2
	v_add_u32_e32 v3, v5, v3
	v_cmp_ne_u32_e32 vcc, v4, v3
	s_and_saveexec_b64 s[6:7], vcc
	s_xor_b64 s[6:7], exec, s[6:7]
	s_cbranch_execz .LBB0_391
	buffer_inv sc1
	v_readlane_b32 s8, v253, 36
	v_readlane_b32 s9, v253, 37
	s_waitcnt lgkmcnt(0)
	s_nop 3
	global_load_dword v1, v99, s[8:9] sc1
	s_waitcnt vmcnt(0)
	v_cmp_eq_u32_e32 vcc, v1, v2
	s_and_saveexec_b64 s[8:9], vcc
	s_cbranch_execz .LBB0_390
	s_mov_b32 s4, 1
	s_mov_b64 s[10:11], 0
	s_branch .LBB0_381

; __device__ __forceinline__ unsigned xb_add(unsigned* p, unsigned v) { return __hip_atomic_fetch_add(p, v, __ATOMIC_RELAXED, __HIP_MEMORY_SCOPE_AGENT); }
; __device__ __forceinline__ void xcd_barrier(const XcdBarrier& b) {
;     ...
;             __builtin_amdgcn_fence(__ATOMIC_ACQUIRE, "agent");
;             xb_add(&bar[XB_XGEN(b.x)], 1u);
;             asm volatile("s_waitcnt vmcnt(0)" ::: "memory");
.LBB0_408:
	s_or_b64 exec, exec, s[6:7]
	s_mov_b64 s[6:7], exec
	v_mbcnt_lo_u32_b32 v1, s6, 0
	v_mbcnt_hi_u32_b32 v1, s7, v1
	v_cmp_eq_u32_e32 vcc, 0, v1
	s_and_saveexec_b64 s[8:9], vcc
	s_cbranch_execz .LBB0_410
	s_bcnt1_i32_b64 s4, s[6:7]
	v_readlane_b32 s6, v253, 36
	v_mov_b32_e32 v1, s4
	v_readlane_b32 s7, v253, 37
	s_nop 4
	global_atomic_add v99, v1, s[6:7]
.LBB0_410:
	s_or_b64 exec, exec, s[8:9]
	buffer_inv sc1
	s_waitcnt vmcnt(0)

; __device__ __forceinline__ unsigned xb_ld(unsigned* p)              { return __hip_atomic_load(p, __ATOMIC_RELAXED, __HIP_MEMORY_SCOPE_AGENT); }
; __device__ __forceinline__ unsigned xb_add(unsigned* p, unsigned v) { return __hip_atomic_fetch_add(p, v, __ATOMIC_RELAXED, __HIP_MEMORY_SCOPE_AGENT); }
; #define XB_SPIN(cond, bar) do { unsigned _sp = 0; while (cond) { __builtin_amdgcn_s_sleep(1); \
;     if ((++_sp & 255u) == 0u) { if (xb_ld(&(bar)[XB_TMO])) break; if (_sp > XB_SPIN_CAP) { atomicAdd(&(bar)[XB_TMO], 1u); break; } } } } while (0)
; __device__ __forceinline__ void xcd_barrier(const XcdBarrier& b) {
;     ...
;         const unsigned old = xb_add(&bar[XB_XSUB(b.x)], 1u);
;         const unsigned gen = old / nloc;
;         if (old + 1u == (gen + 1u) * nloc) {
;             __builtin_amdgcn_fence(__ATOMIC_RELEASE, "agent");
;             asm volatile("s_waitcnt vmcnt(0)" ::: "memory");
;             const unsigned og = xb_add(&bar[XB_TOP], 1u);
;             const unsigned tg = og / nx;
;             if (og + 1u == (tg + 1u) * nx) xb_add(&bar[XB_TOPGEN], 1u);
;             else XB_SPIN(xb_ld(&bar[XB_TOPGEN]) == tg, bar);
;             __builtin_amdgcn_fence(__ATOMIC_ACQUIRE, "agent");
;             xb_add(&bar[XB_XGEN(b.x)], 1u);
;             asm volatile("s_waitcnt vmcnt(0)" ::: "memory");
;         } else {
;             XB_SPIN(xb_ld(&bar[XB_XGEN(b.x)]) == gen, bar);
.LBB0_826:
	s_or_b64 exec, exec, s[6:7]
	v_cvt_f32_u32_e32 v5, v3
	s_waitcnt vmcnt(0)
	v_readfirstlane_b32 s4, v4
	v_sub_u32_e32 v4, 0, v3
	v_rcp_iflag_f32_e32 v5, v5
	v_add_u32_e32 v6, s4, v1
	v_mul_f32_e32 v5, 0x4f7ffffe, v5
	v_cvt_u32_f32_e32 v5, v5
	v_mul_lo_u32 v1, v4, v5
	v_mul_hi_u32 v1, v5, v1
	v_add_u32_e32 v1, v5, v1
	v_mul_hi_u32 v1, v6, v1
	v_mul_lo_u32 v4, v1, v3
	v_sub_u32_e32 v4, v6, v4
	v_add_u32_e32 v5, 1, v1
	v_cmp_ge_u32_e32 vcc, v4, v3
	s_nop 1
	v_cndmask_b32_e32 v1, v1, v5, vcc
	v_sub_u32_e32 v5, v4, v3
	v_cndmask_b32_e32 v4, v4, v5, vcc
	v_add_u32_e32 v5, 1, v1
	v_cmp_ge_u32_e32 vcc, v4, v3
	v_add_u32_e32 v4, 1, v6
	s_nop 0
	v_cndmask_b32_e32 v1, v1, v5, vcc
	v_mul_lo_u32 v5, v3, v1
	v_add_u32_e32 v3, v5, v3
	v_cmp_ne_u32_e32 vcc, v4, v3
	s_and_saveexec_b64 s[6:7], vcc
	s_xor_b64 s[6:7], exec, s[6:7]
	s_cbranch_execz .LBB0_840
	buffer_inv sc1
	v_readlane_b32 s8, v253, 36
	v_readlane_b32 s9, v253, 37
	s_waitcnt lgkmcnt(0)
	s_nop 3
	global_load_dword v2, v99, s[8:9] sc1
	s_waitcnt vmcnt(0)
	v_cmp_eq_u32_e32 vcc, v2, v1
	s_and_saveexec_b64 s[8:9], vcc
	s_cbranch_execz .LBB0_839
	s_mov_b32 s4, 1
	s_mov_b64 s[10:11], 0
	s_branch .LBB0_830

; __device__ __forceinline__ unsigned xb_add(unsigned* p, unsigned v) { return __hip_atomic_fetch_add(p, v, __ATOMIC_RELAXED, __HIP_MEMORY_SCOPE_AGENT); }
; __device__ __forceinline__ void xcd_barrier(const XcdBarrier& b) {
;     ...
;             xb_add(&bar[XB_XGEN(b.x)], 1u);
;             asm volatile("s_waitcnt vmcnt(0)" ::: "memory");
.Lxcd_local_0:
	s_mov_b64 s[6:7], exec
	v_mbcnt_lo_u32_b32 v1, s6, 0
	v_mbcnt_hi_u32_b32 v1, s7, v1
	v_cmp_eq_u32_e32 vcc, 0, v1
	s_and_saveexec_b64 s[8:9], vcc
	s_cbranch_execz .LBB0_859
	s_bcnt1_i32_b64 s4, s[6:7]
	v_readlane_b32 s6, v253, 36
	v_mov_b32_e32 v1, s4
	v_readlane_b32 s7, v253, 37
	s_nop 4
	global_atomic_add v99, v1, s[6:7]

; __device__ __forceinline__ unsigned xb_ld(unsigned* p)              { return __hip_atomic_load(p, __ATOMIC_RELAXED, __HIP_MEMORY_SCOPE_AGENT); }
; __device__ __forceinline__ unsigned xb_add(unsigned* p, unsigned v) { return __hip_atomic_fetch_add(p, v, __ATOMIC_RELAXED, __HIP_MEMORY_SCOPE_AGENT); }
; #define XB_SPIN(cond, bar) do { unsigned _sp = 0; while (cond) { __builtin_amdgcn_s_sleep(1); \
;     if ((++_sp & 255u) == 0u) { if (xb_ld(&(bar)[XB_TMO])) break; if (_sp > XB_SPIN_CAP) { atomicAdd(&(bar)[XB_TMO], 1u); break; } } } } while (0)
; __device__ __forceinline__ void xcd_barrier(const XcdBarrier& b) {
;     ...
;         const unsigned old = xb_add(&bar[XB_XSUB(b.x)], 1u);
;         const unsigned gen = old / nloc;
;         if (old + 1u == (gen + 1u) * nloc) {
;             __builtin_amdgcn_fence(__ATOMIC_RELEASE, "agent");
;             asm volatile("s_waitcnt vmcnt(0)" ::: "memory");
;             const unsigned og = xb_add(&bar[XB_TOP], 1u);
;             const unsigned tg = og / nx;
;             if (og + 1u == (tg + 1u) * nx) xb_add(&bar[XB_TOPGEN], 1u);
;             else XB_SPIN(xb_ld(&bar[XB_TOPGEN]) == tg, bar);
;             __builtin_amdgcn_fence(__ATOMIC_ACQUIRE, "agent");
;             xb_add(&bar[XB_XGEN(b.x)], 1u);
;             asm volatile("s_waitcnt vmcnt(0)" ::: "memory");
;         } else {
;             XB_SPIN(xb_ld(&bar[XB_XGEN(b.x)]) == gen, bar);
.LBB0_1077:
	s_or_b64 exec, exec, s[10:11]
	v_cvt_f32_u32_e32 v5, v3
	s_waitcnt vmcnt(0)
	v_readfirstlane_b32 s4, v4
	v_sub_u32_e32 v4, 0, v3
	v_rcp_iflag_f32_e32 v5, v5
	v_add_u32_e32 v6, s4, v1
	v_mul_f32_e32 v5, 0x4f7ffffe, v5
	v_cvt_u32_f32_e32 v5, v5
	v_mul_lo_u32 v1, v4, v5
	v_mul_hi_u32 v1, v5, v1
	v_add_u32_e32 v1, v5, v1
	v_mul_hi_u32 v1, v6, v1
	v_mul_lo_u32 v4, v1, v3
	v_sub_u32_e32 v4, v6, v4
	v_add_u32_e32 v5, 1, v1
	v_cmp_ge_u32_e32 vcc, v4, v3
	s_nop 1
	v_cndmask_b32_e32 v1, v1, v5, vcc
	v_sub_u32_e32 v5, v4, v3
	v_cndmask_b32_e32 v4, v4, v5, vcc
	v_add_u32_e32 v5, 1, v1
	v_cmp_ge_u32_e32 vcc, v4, v3
	v_add_u32_e32 v4, 1, v6
	s_nop 0
	v_cndmask_b32_e32 v1, v1, v5, vcc
	v_mul_lo_u32 v5, v3, v1
	v_add_u32_e32 v3, v5, v3
	v_cmp_ne_u32_e32 vcc, v4, v3
	s_and_saveexec_b64 s[10:11], vcc
	s_xor_b64 s[10:11], exec, s[10:11]
	s_cbranch_execz .LBB0_1091
	buffer_inv sc1
	v_readlane_b32 s14, v253, 36
	v_readlane_b32 s15, v253, 37
	s_waitcnt lgkmcnt(0)
	s_nop 3
	global_load_dword v2, v99, s[14:15] sc1
	s_waitcnt vmcnt(0)
	v_cmp_eq_u32_e32 vcc, v2, v1
	s_and_saveexec_b64 s[14:15], vcc
	s_cbranch_execz .LBB0_1090
	s_mov_b32 s4, 1
	s_mov_b64 s[34:35], 0
	s_branch .LBB0_1081

; __device__ __forceinline__ unsigned xb_add(unsigned* p, unsigned v) { return __hip_atomic_fetch_add(p, v, __ATOMIC_RELAXED, __HIP_MEMORY_SCOPE_AGENT); }
; __device__ __forceinline__ void xcd_barrier(const XcdBarrier& b) {
;     ...
;             xb_add(&bar[XB_XGEN(b.x)], 1u);
;             asm volatile("s_waitcnt vmcnt(0)" ::: "memory");
.Lxcd_local_2:
	s_mov_b64 s[10:11], exec
	v_mbcnt_lo_u32_b32 v1, s10, 0
	v_mbcnt_hi_u32_b32 v1, s11, v1
	v_cmp_eq_u32_e32 vcc, 0, v1
	s_and_saveexec_b64 s[14:15], vcc
	s_cbranch_execz .LBB0_1110
	s_bcnt1_i32_b64 s4, s[10:11]
	v_readlane_b32 s10, v253, 36
	v_mov_b32_e32 v1, s4
	v_readlane_b32 s11, v253, 37
	s_nop 4
	global_atomic_add v99, v1, s[10:11]
.LBB0_1110:
	s_or_b64 exec, exec, s[14:15]
	buffer_inv sc1
	s_waitcnt vmcnt(0)
